# NORM prompt loop: removed conservative compiler vmcnt waits that defeated the cross-trip prefetch (WAW-paranoia ladders, parameter vmcnt(0) now only when params reloaded, end-of-trip drain -> vmcnt(4)
# speedup vs baseline: 1.0107x; 1.0052x over previous
; #define NORM_XIN(r_) (xf32 ? GIN(c, 0) + (size_t)(r_) * D : c.out + (size_t)(r_) * D)
; __device__ __forceinline__ void norm_load(NormRow& r, const float* xin, const bf16_t* F, const float* PSS, int row, int lane, bool has_upd, bool xf32) {
;     ...
;         for (int j = 0; j < 4; ++j) r.xb[j] = *(const u32x2*)((const bf16_t*)xin + 4 * (lane + 64 * j));
;     }
;     if (has_upd) {
; #pragma unroll
;         for (int j = 0; j < 4; ++j) r.f[j] = *(const u32x2*)(F + (size_t)row * D + 4 * (lane + 64 * j));
;         r.p = PSS[(size_t)row * 16 + (lane & 15)];
; __device__ __forceinline__ void norm_phase(const Ctx& c, int s) {
;     ...
;             NormRow cu[2];
;             cu[0] = nx[0]; cu[1] = nx[1];
;             if (row0 + 2 < re) norm_load(nx[0], NORM_XIN(row0 + 2), F, PSS, row0 + 2, lane, has_upd, xf32);
.LBB0_648:
	s_andn2_b64 vcc, exec, s[6:7]
	v_mov_b64_e32 v[172:173], v[226:227]
	v_mov_b64_e32 v[170:171], v[224:225]
	v_mov_b64_e32 v[168:169], v[222:223]
	v_mov_b64_e32 v[146:147], v[220:221]
	s_cbranch_vccnz .LBB0_650
	v_lshl_add_u64 v[52:53], s[36:37], 0, v[138:139]
	global_load_dwordx2 v[172:173], v[52:53], off
	global_load_dwordx2 v[170:171], v[52:53], off offset:512
	global_load_dwordx2 v[168:169], v[52:53], off offset:1024
	global_load_dwordx2 v[146:147], v[52:53], off offset:1536
	v_mov_b64_e32 v[64:65], v[112:113]
	v_mov_b64_e32 v[60:61], v[108:109]
	v_mov_b64_e32 v[56:57], v[104:105]
	v_mov_b64_e32 v[52:53], v[100:101]
	v_mov_b64_e32 v[66:67], v[114:115]
	v_mov_b64_e32 v[62:63], v[110:111]
	v_mov_b64_e32 v[58:59], v[106:107]
	v_mov_b64_e32 v[54:55], v[102:103]

; #define NORM_XIN(r_) (xf32 ? GIN(c, 0) + (size_t)(r_) * D : c.out + (size_t)(r_) * D)
; __device__ __forceinline__ void norm_load(NormRow& r, const float* xin, const bf16_t* F, const float* PSS, int row, int lane, bool has_upd, bool xf32) {
;     ...
;         for (int j = 0; j < 4; ++j) r.xb[j] = *(const u32x2*)((const bf16_t*)xin + 4 * (lane + 64 * j));
;     }
;     if (has_upd) {
; #pragma unroll
;         for (int j = 0; j < 4; ++j) r.f[j] = *(const u32x2*)(F + (size_t)row * D + 4 * (lane + 64 * j));
;         r.p = PSS[(size_t)row * 16 + (lane & 15)];
; __device__ __forceinline__ void norm_phase(const Ctx& c, int s) {
;     ...
;             cu[0] = nx[0]; cu[1] = nx[1];
;             if (row0 + 2 < re) norm_load(nx[0], NORM_XIN(row0 + 2), F, PSS, row0 + 2, lane, has_upd, xf32);
;             if (row0 + 3 < re) norm_load(nx[1], NORM_XIN(row0 + 3), F, PSS, row0 + 3, lane, has_upd, xf32);
.LBB0_654:
	s_andn2_b64 vcc, exec, s[44:45]
	v_mov_b64_e32 v[192:193], v[210:211]
	v_mov_b64_e32 v[190:191], v[208:209]
	v_mov_b64_e32 v[188:189], v[206:207]
	v_mov_b64_e32 v[186:187], v[200:201]
	s_cbranch_vccnz .LBB0_656
	global_load_dwordx2 v[192:193], v120, s[6:7]
	global_load_dwordx2 v[190:191], v120, s[6:7] offset:512
	global_load_dwordx2 v[188:189], v120, s[6:7] offset:1024
	global_load_dwordx2 v[186:187], v120, s[6:7] offset:1536
	v_mov_b64_e32 v[80:81], v[96:97]
	v_mov_b64_e32 v[76:77], v[92:93]
	v_mov_b64_e32 v[72:73], v[88:89]
	v_mov_b64_e32 v[68:69], v[84:85]
	v_mov_b64_e32 v[82:83], v[98:99]
	v_mov_b64_e32 v[78:79], v[94:95]
	v_mov_b64_e32 v[74:75], v[90:91]
	v_mov_b64_e32 v[70:71], v[86:87]

.LBB0_658:
	s_mov_b32 s32, 1
	s_add_i32 s6, s25, s50
	s_mul_hi_i32 s7, s6, 0x9000
	s_mul_i32 s6, s6, 0x9000
	s_add_u32 s6, s57, s6
	s_addc_u32 s7, s58, s7
	s_add_u32 s46, s6, 0x2000
	s_addc_u32 s47, s7, 0
	s_and_b64 vcc, exec, s[4:5]
	s_cbranch_vccnz .LBB0_660
	global_load_dwordx4 v[36:39], v118, s[46:47]
	global_load_dwordx4 v[238:241], v[130:131], off
	v_mov_b32_e32 v167, v166
	s_waitcnt vmcnt(0)
	v_pk_mul_f32 v[38:39], v[38:39], v[240:241]
	v_pk_mul_f32 v[36:37], v[36:37], v[238:239]
	v_pk_mul_f32 v[38:39], v[166:167], v[38:39]
	v_pk_mul_f32 v[36:37], v[128:129], v[36:37]

.LBB0_692:
	v_cndmask_b32_e64 v119, 0, 1, s[12:13]
	v_cmp_ne_u32_e64 s[6:7], 1, v119
	s_andn2_b64 vcc, exec, s[12:13]
	s_cbranch_vccnz .LBB0_694
	v_pk_mul_f32 v[212:213], v[114:115], v[114:115]
	v_pk_mul_f32 v[214:215], v[112:113], v[112:113]
	v_pk_mov_b32 v[216:217], v[214:215], v[212:213] op_sel:[1,0]
	v_mov_b32_e32 v215, v213
	v_pk_add_f32 v[212:213], v[216:217], v[214:215]
	v_pk_mul_f32 v[214:215], v[110:111], v[110:111]
	v_pk_add_f32 v[212:213], v[212:213], v[212:213] op_sel_hi:[0,1]
	v_pk_mul_f32 v[216:217], v[108:109], v[108:109]
	v_mul_f32_e32 v212, v104, v104
	v_pk_mov_b32 v[218:219], v[216:217], v[214:215] op_sel:[1,0]
	v_mov_b32_e32 v217, v215
	v_pk_add_f32 v[214:215], v[218:219], v[216:217]
	v_pk_fma_f32 v[216:217], v[104:105], v[104:105], v[212:213] op_sel_hi:[1,1,0]
	v_mul_f32_e32 v212, v106, v106
	v_pk_add_f32 v[214:215], v[214:215], v[214:215] op_sel_hi:[0,1]
	v_pk_fma_f32 v[218:219], v[106:107], v[106:107], v[212:213] op_sel_hi:[1,1,0]
	v_mul_f32_e32 v216, v100, v100
	v_mul_f32_e32 v218, v101, v101
	v_mul_f32_e32 v214, v102, v102
	v_mul_f32_e32 v212, v103, v103
	v_pk_add_f32 v[216:217], v[216:217], v[218:219]
	v_pk_add_f32 v[212:213], v[214:215], v[212:213]
	v_pk_add_f32 v[212:213], v[216:217], v[212:213]
	v_pk_mul_f32 v[114:115], v[22:23], v[114:115]
	v_add_f32_e32 v119, v212, v213
	s_nop 1
	v_add_f32_dpp v119, v119, v119 quad_perm:[1,0,3,2] row_mask:0xf bank_mask:0xf
	s_nop 1
	v_add_f32_dpp v119, v119, v119 quad_perm:[2,3,0,1] row_mask:0xf bank_mask:0xf
	s_nop 1
	v_add_f32_dpp v119, v119, v119 row_half_mirror row_mask:0xf bank_mask:0xf
	s_nop 1
	v_add_f32_dpp v119, v119, v119 row_mirror row_mask:0xf bank_mask:0xf
	s_nop 1
	v_add_f32_dpp v119, v119, v119 row_bcast:15 row_mask:0xa bank_mask:0xf
	s_nop 1
	v_add_f32_dpp v119, v119, v119 row_bcast:31 row_mask:0xc bank_mask:0xf
	s_nop 0
	v_readlane_b32 s32, v119, 63
	s_nop 1
	v_mov_b32_e32 v119, s32
	v_pk_mul_f32 v[112:113], v[20:21], v[112:113]
	s_mov_b32 s43, 0x6e88000
	v_pk_mul_f32 v[110:111], v[30:31], v[110:111]
	v_pk_mul_f32 v[108:109], v[28:29], v[108:109]
	v_pk_mul_f32 v[106:107], v[26:27], v[106:107]
	v_pk_mul_f32 v[104:105], v[24:25], v[104:105]
	v_pk_mul_f32 v[102:103], v[34:35], v[102:103]
	v_pk_mul_f32 v[100:101], v[32:33], v[100:101]
	v_fmamk_f32 v119, v119, 0x3a800000, v228
	v_mul_f32_e32 v121, 0x4b800000, v119
	v_cmp_gt_f32_e32 vcc, s62, v119
	s_nop 1
	v_cndmask_b32_e32 v119, v119, v121, vcc
	v_rsq_f32_e32 v119, v119
	s_nop 0
	v_mul_f32_e32 v121, 0x45800000, v119
	v_cndmask_b32_e32 v212, v119, v121, vcc
	s_cmp_eq_u32 s32, 0
	s_cbranch_scc1 .Lnorm_nw_a
	s_waitcnt vmcnt(0)
.Lnorm_nw_a:
	v_pk_fma_f32 v[114:115], v[114:115], v[212:213], v[6:7] op_sel_hi:[1,0,1]
	v_pk_fma_f32 v[112:113], v[112:113], v[212:213], v[4:5] op_sel_hi:[1,0,1]
	v_pk_fma_f32 v[110:111], v[110:111], v[212:213], v[14:15] op_sel_hi:[1,0,1]
	v_cvt_pk_bf16_f32 v112, v112, v113
	v_cvt_pk_bf16_f32 v113, v114, v115
	v_lshl_add_u64 v[114:115], s[26:27], 0, v[138:139]
	v_add_co_u32_e32 v114, vcc, s43, v114
	v_pk_fma_f32 v[108:109], v[108:109], v[212:213], v[12:13] op_sel_hi:[1,0,1]
	v_pk_fma_f32 v[106:107], v[106:107], v[212:213], v[10:11] op_sel_hi:[1,0,1]
	v_pk_fma_f32 v[104:105], v[104:105], v[212:213], v[8:9] op_sel_hi:[1,0,1]
	v_pk_fma_f32 v[102:103], v[102:103], v[212:213], v[18:19] op_sel_hi:[1,0,1]
	v_pk_fma_f32 v[100:101], v[100:101], v[212:213], v[16:17] op_sel_hi:[1,0,1]
	v_addc_co_u32_e32 v115, vcc, 0, v115, vcc
	v_cvt_pk_bf16_f32 v108, v108, v109
	v_cvt_pk_bf16_f32 v109, v110, v111
	v_cvt_pk_bf16_f32 v104, v104, v105
	v_cvt_pk_bf16_f32 v105, v106, v107
	v_cvt_pk_bf16_f32 v100, v100, v101
	v_cvt_pk_bf16_f32 v101, v102, v103
	global_store_dwordx2 v[114:115], v[112:113], off
	global_store_dwordx2 v[114:115], v[108:109], off offset:512
	global_store_dwordx2 v[114:115], v[104:105], off offset:1024
	global_store_dwordx2 v[114:115], v[100:101], off offset:1536
.LBB0_694:
	s_cmp_ge_i32 s24, s16
	s_cbranch_scc1 .LBB0_705
	s_ashr_i32 s51, s24, 12
	s_cmp_eq_u32 s51, s25
	s_cbranch_scc1 .LBB0_706
	s_mov_b32 s32, 1
	s_add_i32 s25, s51, s50
	s_mul_hi_i32 s43, s25, 0x9000
	s_mul_i32 s25, s25, 0x9000
	s_add_u32 s25, s57, s25
	s_addc_u32 s43, s58, s43
	s_add_u32 s46, s25, 0x2000
	s_addc_u32 s47, s43, 0
	s_and_b64 vcc, exec, s[4:5]
	s_cbranch_vccnz .LBB0_698
	global_load_dwordx4 v[36:39], v118, s[46:47]
	global_load_dwordx4 v[100:103], v[130:131], off
	v_mov_b32_e32 v167, v166
	s_waitcnt vmcnt(0)
	v_pk_mul_f32 v[38:39], v[38:39], v[102:103]
	v_pk_mul_f32 v[36:37], v[36:37], v[100:101]
	v_pk_mul_f32 v[38:39], v[166:167], v[38:39]
	v_pk_mul_f32 v[36:37], v[128:129], v[36:37]

; #define NORM_XIN(r_) (xf32 ? GIN(c, 0) + (size_t)(r_) * D : c.out + (size_t)(r_) * D)
; __device__ __forceinline__ void norm_phase(const Ctx& c, int s) {
;     ...
;         for (int row0 = rb; row0 < re; row0 += 2) {
;             NormRow cu[2];
;             cu[0] = nx[0]; cu[1] = nx[1];
;             if (row0 + 2 < re) norm_load(nx[0], NORM_XIN(row0 + 2), F, PSS, row0 + 2, lane, has_upd, xf32);
;             if (row0 + 3 < re) norm_load(nx[1], NORM_XIN(row0 + 3), F, PSS, row0 + 3, lane, has_upd, xf32);
.LBB0_717:
	v_pk_mul_f32 v[100:101], v[98:99], v[98:99]
	v_pk_mul_f32 v[102:103], v[96:97], v[96:97]
	s_ashr_i32 s25, s24, 31
	v_pk_mov_b32 v[104:105], v[102:103], v[100:101] op_sel:[1,0]
	v_mov_b32_e32 v103, v101
	v_pk_add_f32 v[100:101], v[104:105], v[102:103]
	v_pk_mul_f32 v[102:103], v[94:95], v[94:95]
	v_pk_add_f32 v[100:101], v[100:101], v[100:101] op_sel_hi:[0,1]
	v_pk_mul_f32 v[104:105], v[92:93], v[92:93]
	v_mul_f32_e32 v100, v88, v88
	v_pk_mov_b32 v[106:107], v[104:105], v[102:103] op_sel:[1,0]
	v_mov_b32_e32 v105, v103
	v_pk_add_f32 v[102:103], v[106:107], v[104:105]
	v_pk_fma_f32 v[104:105], v[88:89], v[88:89], v[100:101] op_sel_hi:[1,1,0]
	v_mul_f32_e32 v100, v90, v90
	v_pk_add_f32 v[102:103], v[102:103], v[102:103] op_sel_hi:[0,1]
	v_pk_fma_f32 v[106:107], v[90:91], v[90:91], v[100:101] op_sel_hi:[1,1,0]
	v_mul_f32_e32 v104, v84, v84
	v_mul_f32_e32 v106, v85, v85
	v_mul_f32_e32 v102, v86, v86
	v_mul_f32_e32 v100, v87, v87
	v_pk_add_f32 v[104:105], v[104:105], v[106:107]
	v_pk_add_f32 v[100:101], v[102:103], v[100:101]
	v_pk_add_f32 v[100:101], v[104:105], v[100:101]
	v_pk_mul_f32 v[98:99], v[22:23], v[98:99]
	v_add_f32_e32 v100, v100, v101
	v_pk_mul_f32 v[96:97], v[20:21], v[96:97]
	v_pk_mul_f32 v[94:95], v[30:31], v[94:95]
	s_nop 1
	v_add_f32_dpp v100, v100, v100 quad_perm:[1,0,3,2] row_mask:0xf bank_mask:0xf
	s_nop 1
	v_add_f32_dpp v100, v100, v100 quad_perm:[2,3,0,1] row_mask:0xf bank_mask:0xf
	s_nop 1
	v_add_f32_dpp v100, v100, v100 row_half_mirror row_mask:0xf bank_mask:0xf
	s_nop 1
	v_add_f32_dpp v100, v100, v100 row_mirror row_mask:0xf bank_mask:0xf
	s_nop 1
	v_add_f32_dpp v100, v100, v100 row_bcast:15 row_mask:0xa bank_mask:0xf
	s_nop 1
	v_add_f32_dpp v100, v100, v100 row_bcast:31 row_mask:0xc bank_mask:0xf
	s_nop 0
	v_readlane_b32 s32, v100, 63
	s_nop 1
	v_mov_b32_e32 v100, s32
	v_pk_mul_f32 v[92:93], v[28:29], v[92:93]
	v_pk_mul_f32 v[90:91], v[26:27], v[90:91]
	v_pk_mul_f32 v[88:89], v[24:25], v[88:89]
	v_pk_mul_f32 v[86:87], v[34:35], v[86:87]
	v_pk_mul_f32 v[84:85], v[32:33], v[84:85]
	s_lshl_b64 s[6:7], s[24:25], 11
	v_fmamk_f32 v100, v100, 0x3a800000, v228
	v_mul_f32_e32 v101, 0x4b800000, v100
	v_cmp_gt_f32_e32 vcc, s62, v100
	s_nop 1
	v_cndmask_b32_e32 v100, v100, v101, vcc
	v_rsq_f32_e32 v100, v100
	s_nop 0
	v_mul_f32_e32 v101, 0x45800000, v100
	v_cndmask_b32_e32 v100, v100, v101, vcc
	s_cmp_eq_u32 s32, 0
	s_cbranch_scc1 .Lnorm_nw_b
	s_waitcnt vmcnt(0)
.Lnorm_nw_b:
	v_pk_fma_f32 v[98:99], v[98:99], v[100:101], v[6:7] op_sel_hi:[1,0,1]
	v_pk_fma_f32 v[96:97], v[96:97], v[100:101], v[4:5] op_sel_hi:[1,0,1]
	v_pk_fma_f32 v[94:95], v[94:95], v[100:101], v[14:15] op_sel_hi:[1,0,1]
	v_pk_fma_f32 v[92:93], v[92:93], v[100:101], v[12:13] op_sel_hi:[1,0,1]
	v_pk_fma_f32 v[90:91], v[90:91], v[100:101], v[10:11] op_sel_hi:[1,0,1]
	v_pk_fma_f32 v[88:89], v[88:89], v[100:101], v[8:9] op_sel_hi:[1,0,1]
	v_pk_fma_f32 v[86:87], v[86:87], v[100:101], v[18:19] op_sel_hi:[1,0,1]
	v_pk_fma_f32 v[84:85], v[84:85], v[100:101], v[16:17] op_sel_hi:[1,0,1]
	v_cvt_pk_bf16_f32 v96, v96, v97
	v_cvt_pk_bf16_f32 v97, v98, v99
	v_lshl_add_u64 v[98:99], v[136:137], 0, s[6:7]
	v_cvt_pk_bf16_f32 v92, v92, v93
	v_cvt_pk_bf16_f32 v93, v94, v95
	v_cvt_pk_bf16_f32 v88, v88, v89
	v_cvt_pk_bf16_f32 v89, v90, v91
	v_cvt_pk_bf16_f32 v84, v84, v85
	v_cvt_pk_bf16_f32 v85, v86, v87
	global_store_dwordx2 v[98:99], v[96:97], off
	global_store_dwordx2 v[98:99], v[92:93], off offset:512
	global_store_dwordx2 v[98:99], v[88:89], off offset:1024
	global_store_dwordx2 v[98:99], v[84:85], off offset:1536
.LBB0_718:
	s_add_u32 s26, s26, 0x1000
	s_addc_u32 s27, s27, 0
	s_add_u32 s36, s36, 0x2000
	s_addc_u32 s37, s37, 0
	s_add_u32 s38, s38, 0x2000
	s_addc_u32 s39, s39, 0
	s_add_i32 s6, s42, -1
	s_add_u32 s40, s40, 0x1000
	s_addc_u32 s41, s41, 0
	s_cmp_lt_i32 s6, s16
	v_lshl_add_u64 v[142:143], v[142:143], 0, s[0:1]
	s_cbranch_scc0 .LBB0_739
	s_waitcnt vmcnt(4)
	s_mov_b32 s32, 0
	v_mov_b64_e32 v[114:115], v[66:67]
	v_mov_b64_e32 v[110:111], v[62:63]
	v_mov_b64_e32 v[106:107], v[58:59]
	v_mov_b64_e32 v[102:103], v[54:55]
	v_mov_b64_e32 v[98:99], v[82:83]
	v_mov_b64_e32 v[94:95], v[78:79]
	v_mov_b64_e32 v[90:91], v[74:75]
	v_mov_b64_e32 v[86:87], v[70:71]
	s_mov_b32 s24, s42
	v_mov_b64_e32 v[112:113], v[64:65]
	v_mov_b64_e32 v[108:109], v[60:61]
	v_mov_b64_e32 v[104:105], v[56:57]
	v_mov_b64_e32 v[100:101], v[52:53]
	v_mov_b64_e32 v[226:227], v[172:173]
	v_mov_b64_e32 v[224:225], v[170:171]
	v_mov_b64_e32 v[222:223], v[168:169]
	v_mov_b64_e32 v[220:221], v[146:147]
	v_mov_b64_e32 v[218:219], v[182:183]
	v_mov_b64_e32 v[216:217], v[178:179]
	v_mov_b64_e32 v[214:215], v[176:177]
	v_mov_b64_e32 v[212:213], v[174:175]
	v_mov_b32_e32 v125, v1
	v_mov_b64_e32 v[96:97], v[80:81]
	v_mov_b64_e32 v[92:93], v[76:77]
	v_mov_b64_e32 v[88:89], v[72:73]
	v_mov_b64_e32 v[84:85], v[68:69]
	v_mov_b64_e32 v[210:211], v[192:193]
	v_mov_b64_e32 v[208:209], v[190:191]
	v_mov_b64_e32 v[206:207], v[188:189]
	v_mov_b64_e32 v[200:201], v[186:187]
	v_mov_b64_e32 v[194:195], v[204:205]
	v_mov_b64_e32 v[184:185], v[202:203]
	v_mov_b64_e32 v[180:181], v[198:199]
	v_mov_b64_e32 v[144:145], v[196:197]
	v_mov_b32_e32 v123, v3
	s_add_i32 s6, s24, 1
	s_cmp_ge_i32 s6, s16
	s_cbranch_scc1 .LBB0_643
	s_branch .LBB0_646
.LBB0_720:
	v_lshl_add_u64 v[68:69], s[40:41], 0, v[138:139]
	v_add_co_u32_e32 v68, vcc, 0x16608000, v68
	s_nop 1
	v_addc_co_u32_e32 v69, vcc, 0, v69, vcc
	global_load_dwordx2 v[182:183], v[68:69], off
	global_load_dwordx2 v[178:179], v[68:69], off offset:512
	global_load_dwordx2 v[176:177], v[68:69], off offset:1024
	global_load_dwordx2 v[174:175], v[68:69], off offset:1536
	global_load_dword v1, v[142:143], off
	s_add_i32 s42, s24, 2
	s_cmp_ge_i32 s42, s16
	v_mov_b32_e32 v3, v123
	s_cbranch_scc1 .LBB0_644
	s_branch .LBB0_652
